# v33 + L3 attention item start: sink logit fetched with s_load_dword (lgkmcnt) instead of global_load + vmcnt(0), which had drained the previous item's output stores before the Q loads could issue
# speedup vs baseline: 1.0020x; 1.0020x over previous
.LBB0_312:
	s_lshl_b32 s3, s4, 8
	s_ashr_i32 s8, s4, 4
	s_and_b32 s3, s3, 0xf00
	s_addk_i32 s4, 0xf800
	s_and_b64 s[10:11], s[0:1], exec
	s_cselect_b32 s4, s8, s4
	s_cselect_b32 s10, s3, 0
	s_ashr_i32 s8, s4, 31
	s_lshr_b32 s8, s8, 28
	s_add_i32 s8, s4, s8
	s_ashr_i32 s24, s8, 4
	s_and_b32 s8, s8, -16
	s_lshl_b32 s25, s24, 12
	s_sub_i32 s4, s4, s8
	v_add_u32_e32 v150, s10, v141
	s_addk_i32 s25, 0x2000
	s_lshl_b32 s10, s24, 8
	s_and_b64 s[0:1], s[0:1], exec
	s_cselect_b32 s0, s25, s10
	v_add_u32_e32 v0, s0, v150
	s_ashr_i32 s28, s4, 2
	s_lshl_b32 s30, s12, 1
	v_readlane_b32 s0, v243, 9
	v_readlane_b32 s1, v243, 10
	s_add_u32 s8, s0, s30
	s_addc_u32 s11, s1, 0
	s_lshl_b32 s0, s24, 2
	s_add_i32 s0, s0, s28
	s_mul_i32 s0, s0, s5
	s_ashr_i32 s1, s0, 31
	s_lshl_b64 s[36:37], s[0:1], 12
	s_add_u32 s0, s8, s36
	s_addc_u32 s1, s11, s37
	s_ashr_i32 s5, s4, 31
	s_lshl_b64 s[12:13], s[4:5], 2
	s_add_u32 s12, s88, s12
	s_addc_u32 s13, s89, s13
	v_or_b32_e32 v106, v0, v140
	s_load_dword s100, s[12:13], 0x0
	s_nop 0
	s_mov_b64 s[12:13], -1
	s_and_b64 vcc, exec, s[6:7]
	v_ashrrev_i32_e32 v107, 31, v106
	s_waitcnt lgkmcnt(0)
	v_mov_b32_e32 v0, s100
	v_mul_f32_e32 v151, 0x3fb8aa3b, v0
	s_cbranch_vccz .LBB0_326
	v_mov_b32_e32 v4, v147
	v_lshlrev_b64 v[2:3], 11, v[106:107]
	s_lshl_b32 s6, s4, 6
	v_lshl_add_u64 v[2:3], s[94:95], 0, v[2:3]
	v_lshlrev_b32_e32 v0, 1, v4
	s_ashr_i32 s7, s6, 31
	v_bfe_u32 v149, v4, 5, 1
	v_and_b32_e32 v16, 8, v0
	v_lshrrev_b32_e32 v0, 1, v4
	v_lshl_add_u64 v[2:3], s[6:7], 1, v[2:3]
	s_ashr_i32 s11, s10, 31
	v_and_b32_e32 v17, 4, v0
	v_lshlrev_b32_e32 v0, 4, v149
	s_lshl_b64 s[38:39], s[10:11], 9
	v_lshl_add_u64 v[2:3], v[2:3], 0, v[0:1]
	s_add_u32 s5, s50, s38
	global_load_dwordx4 v[66:69], v[2:3], off
	global_load_dwordx4 v[70:73], v[2:3], off offset:32
	global_load_dwordx4 v[74:77], v[2:3], off offset:64
	global_load_dwordx4 v[78:81], v[2:3], off offset:96
	v_ashrrev_i32_e32 v2, 31, v4
	s_addc_u32 s8, s51, s39
	s_lshl_b32 s10, s28, 6
	v_add_u32_sdwa v2, v4, v2 dst_sel:DWORD dst_unused:UNUSED_PAD src0_sel:DWORD src1_sel:BYTE_3
	s_ashr_i32 s11, s10, 31
	v_ashrrev_i32_e32 v3, 8, v2
	v_and_b32_e32 v2, 0xffffff00, v2
	s_lshl_b64 s[40:41], s[10:11], 1
	v_ashrrev_i32_e32 v10, 3, v4
	v_sub_u32_e32 v2, v4, v2
	s_add_u32 s10, s5, s40
	v_lshlrev_b32_e32 v5, 11, v3
	v_ashrrev_i32_e32 v2, 2, v2
	v_ashrrev_i32_e32 v11, 31, v10
	s_addc_u32 s11, s8, s41
	v_and_b32_e32 v18, 19, v4
	v_and_b32_e32 v19, 3, v4
	v_and_b32_e32 v54, 31, v4
	v_lshl_add_u32 v5, v2, 5, v5
	v_lshl_add_u32 v2, v3, 6, v2
	s_movk_i32 s31, 0x50
	v_lshlrev_b64 v[52:53], 9, v[10:11]
	v_lshlrev_b32_e32 v4, 4, v4
	v_lshl_or_b32 v6, v19, 3, v5
	v_mul_lo_u32 v20, v2, s31
	v_lshl_add_u64 v[2:3], s[10:11], 0, v[52:53]
	v_and_b32_e32 v110, 0x70, v4
	v_mov_b32_e32 v111, v1
	v_lshl_add_u64 v[12:13], v[2:3], 0, v[110:111]
	v_ashrrev_i32_e32 v7, 31, v6
	s_barrier
	global_load_dwordx4 v[2:5], v[12:13], off
	v_lshlrev_b64 v[50:51], 1, v[6:7]
	v_lshl_add_u64 v[14:15], s[0:1], 0, v[50:51]
	global_load_dwordx4 v[6:9], v[14:15], off
	v_mul_lo_u32 v111, v10, s76
	v_add_u32_e32 v55, v111, v110
	s_mov_b32 s5, 0x8000
	v_lshl_add_u32 v152, v19, 4, v20
	s_movk_i32 s8, 0x2000
	s_mov_b32 s10, s9
	s_mov_b32 s11, s9
	s_mov_b32 s12, s9
	s_mov_b32 s13, s9
	s_mov_b32 s14, s9
	s_mov_b32 s15, s9
	s_mov_b32 s16, s9
	s_mov_b32 s17, s9
	s_mov_b32 s18, s9
	s_mov_b32 s19, s9
	s_mov_b32 s20, s9
	s_mov_b32 s21, s9
	s_mov_b32 s22, s9
	s_mov_b32 s23, s9
	v_lshlrev_b64 v[108:109], 10, v[106:107]
	s_mov_b32 s29, 1
	v_mad_u32_u24 v157, v54, s31, v0
	s_waitcnt vmcnt(1)
	ds_write_b128 v55, v[2:5]
	v_add_co_u32_e32 v2, vcc, s5, v12
	s_waitcnt vmcnt(0)
	ds_write_b128 v152, v[6:9] offset:9216
	v_addc_co_u32_e32 v3, vcc, 0, v13, vcc
	s_waitcnt lgkmcnt(0)
	s_barrier
	global_load_dwordx4 v[82:85], v[2:3], off
	v_add_co_u32_e32 v2, vcc, s8, v14
	s_mov_b32 s8, s9
	s_nop 0
	v_addc_co_u32_e32 v3, vcc, 0, v15, vcc
	global_load_dwordx4 v[86:89], v[2:3], off
	v_or3_b32 v2, v18, v16, v17
	v_mad_u32_u24 v153, v2, s76, v0
	ds_read_b128 v[34:37], v153 offset:4608
	ds_read_b128 v[18:21], v153
	ds_read_b128 v[38:41], v153 offset:32
	s_waitcnt lgkmcnt(1)
	v_mfma_f32_32x32x16_bf16 v[18:33], v[18:21], v[66:69], 0
	ds_read_b128 v[56:59], v153 offset:4640
	v_cmp_lt_i32_e32 vcc, v198, v200
	v_mov_b64_e32 v[2:3], s[8:9]
	v_mov_b64_e32 v[4:5], s[10:11]
	v_mov_b64_e32 v[6:7], s[12:13]
	v_mov_b64_e32 v[8:9], s[14:15]
	v_mov_b64_e32 v[10:11], s[16:17]
	s_waitcnt lgkmcnt(1)
	v_mfma_f32_32x32x16_bf16 v[18:33], v[38:41], v[70:73], v[18:33]
	ds_read_b128 v[38:41], v153 offset:64
	ds_read_b128 v[60:63], v153 offset:4672
	v_mov_b64_e32 v[12:13], s[18:19]
	v_mov_b64_e32 v[14:15], s[20:21]
	v_mov_b64_e32 v[16:17], s[22:23]
	v_readlane_b32 s8, v242, 49
	s_add_u32 s10, s8, s40
	v_readlane_b32 s8, v242, 50
	s_waitcnt lgkmcnt(1)
	v_mfma_f32_32x32x16_bf16 v[18:33], v[38:41], v[74:77], v[18:33]
	ds_read_b128 v[38:41], v153 offset:96
	ds_read_b128 v[90:93], v153 offset:4704
	s_addc_u32 s11, s8, s41
	s_add_u32 s8, s36, s30
	s_mov_b32 s5, 0
	s_waitcnt vmcnt(1)
	ds_write_b128 v55, v[82:85] offset:19456
	s_waitcnt vmcnt(0)
	ds_write_b128 v152, v[86:89] offset:28672
	s_waitcnt lgkmcnt(3)
	v_mfma_f32_32x32x16_bf16 v[18:33], v[38:41], v[78:81], v[18:33]
	s_waitcnt lgkmcnt(0)
	s_barrier
	s_nop 9
	v_max_f32_e32 v38, v19, v19
	v_max_f32_e32 v39, v18, v18
	v_max_f32_e32 v38, v39, v38
	v_max3_f32 v38, v38, v20, v21
	v_max3_f32 v38, v38, v22, v23
	v_max3_f32 v38, v38, v24, v25
	v_max3_f32 v38, v38, v26, v27
	v_max3_f32 v38, v38, v28, v29
	v_max3_f32 v38, v38, v30, v31
	v_max3_f32 v64, v38, v32, v33
	v_mfma_f32_32x32x16_bf16 v[34:49], v[34:37], v[66:69], 0
	v_mfma_f32_32x32x16_bf16 v[34:49], v[56:59], v[70:73], v[34:49]
	v_cndmask_b32_e32 v57, v197, v198, vcc
	v_lshlrev_b32_e32 v154, 2, v57
	v_mfma_f32_32x32x16_bf16 v[34:49], v[60:63], v[74:77], v[34:49]
	v_mfma_f32_32x32x16_bf16 v[34:49], v[90:93], v[78:81], v[34:49]
	s_nop 11
	v_max3_f32 v56, v64, v34, v35
	v_max3_f32 v56, v56, v36, v37
	v_max3_f32 v56, v56, v38, v39
	v_max3_f32 v56, v56, v40, v41
	v_max3_f32 v56, v56, v42, v43
	v_max3_f32 v56, v56, v44, v45
	v_max3_f32 v56, v56, v46, v47
	v_max3_f32 v56, v56, v48, v49
	ds_bpermute_b32 v57, v154, v56
	s_waitcnt lgkmcnt(0)
	v_max3_f32 v156, v151, v56, v57
	v_sub_f32_e32 v18, v18, v156
	v_exp_f32_e32 v116, v18
	v_sub_f32_e32 v18, v34, v156
	v_exp_f32_e32 v120, v18
	v_sub_f32_e32 v18, v19, v156
	v_exp_f32_e32 v117, v18
	v_sub_f32_e32 v18, v35, v156
	v_exp_f32_e32 v121, v18
	v_sub_f32_e32 v18, v20, v156
	v_exp_f32_e32 v118, v18
	v_sub_f32_e32 v18, v36, v156
	v_exp_f32_e32 v122, v18
	v_sub_f32_e32 v18, v21, v156
	v_exp_f32_e32 v119, v18
	v_sub_f32_e32 v18, v37, v156
	v_exp_f32_e32 v123, v18
	v_sub_f32_e32 v18, v22, v156
	v_exp_f32_e32 v104, v18
	v_sub_f32_e32 v18, v38, v156
	v_exp_f32_e32 v96, v18
	v_sub_f32_e32 v18, v23, v156
	v_exp_f32_e32 v105, v18
	v_sub_f32_e32 v18, v39, v156
	v_exp_f32_e32 v97, v18
	v_sub_f32_e32 v18, v24, v156
	v_exp_f32_e32 v124, v18
	v_sub_f32_e32 v18, v40, v156
	v_exp_f32_e32 v132, v18
	v_sub_f32_e32 v18, v25, v156
	v_exp_f32_e32 v125, v18
	v_sub_f32_e32 v18, v41, v156
	v_exp_f32_e32 v133, v18
	v_sub_f32_e32 v18, v26, v156
	v_exp_f32_e32 v126, v18
	v_sub_f32_e32 v18, v42, v156
	v_exp_f32_e32 v134, v18
	v_sub_f32_e32 v18, v27, v156
	v_exp_f32_e32 v127, v18
	v_sub_f32_e32 v18, v43, v156
	v_exp_f32_e32 v135, v18
	v_sub_f32_e32 v18, v28, v156
	v_exp_f32_e32 v128, v18
	v_sub_f32_e32 v18, v44, v156
	v_exp_f32_e32 v136, v18
	v_sub_f32_e32 v18, v29, v156
	v_exp_f32_e32 v129, v18
	v_sub_f32_e32 v18, v45, v156
	v_exp_f32_e32 v137, v18
	v_sub_f32_e32 v18, v30, v156
	v_exp_f32_e32 v100, v18
	v_sub_f32_e32 v18, v46, v156
	v_exp_f32_e32 v92, v18
	v_sub_f32_e32 v18, v31, v156
	v_exp_f32_e32 v101, v18
	v_sub_f32_e32 v18, v47, v156
	v_exp_f32_e32 v93, v18
	v_sub_f32_e32 v18, v32, v156
	v_exp_f32_e32 v130, v18
	v_sub_f32_e32 v18, v48, v156
	v_exp_f32_e32 v138, v18
	v_sub_f32_e32 v18, v33, v156
	v_exp_f32_e32 v131, v18
	v_sub_f32_e32 v18, v49, v156
	v_sub_f32_e32 v56, v151, v156
	v_exp_f32_e32 v139, v18
	v_lshl_add_u64 v[18:19], v[52:53], 0, s[38:39]
	v_exp_f32_e32 v56, v56
	v_or_b32_e32 v18, v18, v110
	v_lshl_add_u64 v[112:113], s[10:11], 0, v[18:19]
	s_addc_u32 s11, s37, 0
	v_readlane_b32 s10, v242, 51
	s_add_u32 s10, s10, s8
	v_readlane_b32 s8, v242, 52
	s_addc_u32 s11, s8, s11
	v_mov_b64_e32 v[32:33], v[16:17]
	v_mul_f32_e32 v155, v148, v56
	v_lshl_add_u64 v[114:115], s[10:11], 0, v[50:51]
	s_mov_b64 s[10:11], 0
	v_mov_b64_e32 v[30:31], v[14:15]
	v_mov_b64_e32 v[28:29], v[12:13]
	v_mov_b64_e32 v[26:27], v[10:11]
	v_mov_b64_e32 v[24:25], v[8:9]
	v_mov_b64_e32 v[22:23], v[6:7]
	v_mov_b64_e32 v[20:21], v[4:5]
	v_mov_b64_e32 v[18:19], v[2:3]
	v_xor_b32_e32 v220, 0x80000000, v156
	v_mov_b32_e32 v221, v220
	v_mov_b32_e32 v222, v220
	v_mov_b32_e32 v223, v220
	v_mov_b32_e32 v224, v220
	v_mov_b32_e32 v225, v220
	v_mov_b32_e32 v226, v220
	v_mov_b32_e32 v227, v220
	v_mov_b32_e32 v228, v220
	v_mov_b32_e32 v229, v220
	v_mov_b32_e32 v230, v220
	v_mov_b32_e32 v231, v220
	v_mov_b32_e32 v232, v220
	v_mov_b32_e32 v233, v220
	v_mov_b32_e32 v234, v220
	v_mov_b32_e32 v235, v220
